# scan: step D split across wave halves - waves 4-7 run D for tokens 0-31 under chunks 2,3 of step C (mid-C barrier), waves 0-3 run D for tokens 32-63 after C; C waves at setprio 2
# speedup vs baseline: 1.0078x; 1.0078x over previous
.LBB0_537:
	s_or_b64 exec, exec, s[0:1]
	s_and_b64 s[0:1], s[36:37], exec
	s_cselect_b32 s28, 16, 0x1000
	s_add_u32 s64, s76, 0x13d00000
	s_addc_u32 s65, s77, 0
	s_bfe_u32 s68, s96, 0x20006
	s_mul_i32 s0, s68, 0x3700
	s_add_i32 s71, s0, 0
	s_and_b32 s0, s96, 0xffffff00
	s_lshr_b32 s74, s96, 8
	s_add_i32 s84, s0, 0
	s_lshl_b32 s11, s74, 5
	s_add_i32 s80, s84, 0x12600
	s_cmpk_lt_u32 s96, 0x540
	v_readlane_b32 s20, v255, 31
	s_cselect_b64 s[40:41], -1, 0
	s_add_i32 s12, s20, -4
	s_lshl_b32 s13, s12, 2
	s_lshl_b32 s22, s12, 10
	s_cmpk_lt_u32 s96, 0x440
	s_cselect_b64 s[42:43], -1, 0
	s_lshl_b32 s66, s20, 10
	s_cmpk_lt_u32 s96, 0x340
	s_cselect_b64 s[46:47], -1, 0
	s_add_i32 s14, s20, 4
	s_lshl_b32 s15, s14, 2
	s_lshl_b32 s23, s14, 10
	s_cmpk_lt_u32 s96, 0x240
	s_cselect_b64 s[48:49], -1, 0
	s_add_i32 s16, s20, 8
	s_lshl_b32 s17, s16, 2
	s_lshl_b32 s24, s16, 10
	s_cmp_eq_u32 s20, 4
	s_cselect_b64 s[50:51], -1, 0
	s_cmp_eq_u32 s20, 2
	s_mov_b32 s0, 0xfc00000
	s_cselect_b32 s38, s0, 0x13d00000
	s_add_u32 s8, s76, s6
	s_addc_u32 s9, s77, 0
	s_mul_i32 s0, s20, 0x2400
	s_add_i32 s1, 0, 0x1a900
	s_add_i32 s81, s1, s0
	s_lshl_b32 s0, s74, 7
	s_add_i32 s83, s0, 0
	s_add_i32 s82, s81, 0x2000
	s_add_i32 s83, s83, 0x14800
	s_add_i32 s84, s84, 0x12400
	s_lshl_b32 s29, s20, 5
	s_add_u32 s6, s64, s6
	s_addc_u32 s7, s65, 0
	s_lshl_b32 s85, s33, 10
	s_add_u32 s18, s76, 0x10000
	v_writelane_b32 v255, s96, 33
	s_addc_u32 s19, s77, 0
	v_lshl_or_b32 v11, s68, 4, v9
	v_writelane_b32 v255, s18, 34
	v_add_u32_e32 v25, 1, v11
	v_lshlrev_b32_e32 v27, 3, v38
	v_writelane_b32 v255, s19, 35
	v_lshlrev_b32_e32 v10, 7, v25
	v_and_b32_e32 v22, 8, v27
	s_add_i32 s0, 0, 0x1cd00
	s_add_i32 s18, 0, 0x1f100
	v_add3_u32 v91, s1, v10, v22
	v_add3_u32 v92, s0, v10, v22
	v_add3_u32 v93, s18, v10, v22
	v_lshlrev_b32_e32 v10, 8, v25
	s_add_i32 s19, 0, 0x23900
	v_add3_u32 v28, s19, v10, v22
	v_lshlrev_b32_e32 v10, 7, v11
	v_add3_u32 v94, s1, v10, v22
	v_add3_u32 v95, s0, v10, v22
	v_add3_u32 v96, s18, v10, v22
	v_lshlrev_b32_e32 v10, 8, v11
	v_add3_u32 v29, s19, v10, v22
	v_add_u32_e32 v10, 1, v89
	s_add_i32 s19, 0, 0x21500
	v_lshl_add_u32 v32, v10, 7, s19
	v_xor_b32_e32 v10, v10, v39
	v_lshlrev_b32_e32 v10, 4, v10
	v_and_b32_e32 v33, 0x70, v10
	v_lshlrev_b32_e32 v10, 7, v89
	v_add_u32_e32 v34, s19, v10
	s_add_i32 s19, 0, 0x12800
	s_cmp_lg_u32 s12, 16
	v_add_u32_e32 v36, s19, v10
	v_or_b32_e32 v10, s13, v38
	s_cselect_b64 vcc, -1, 0
	v_xor_b32_e32 v22, v89, v39
	v_cndmask_b32_e32 v98, 64, v10, vcc
	v_bitop3_b32 v10, v38, v39, s13 bitop3:0x36
	v_lshlrev_b32_e32 v22, 4, v22
	v_and_or_b32 v10, v10, 7, v41
	v_and_b32_e32 v35, 0x70, v22
	v_lshlrev_b32_e32 v22, 4, v10
	v_mov_b32_e32 v10, 0
	v_mov_b32_e32 v23, v10
	s_cmp_lg_u32 s20, 16
	v_lshl_add_u64 v[48:49], s[4:5], 0, v[22:23]
	v_or_b32_e32 v22, s3, v38
	s_cselect_b64 vcc, -1, 0
	v_cndmask_b32_e32 v99, 64, v22, vcc
	v_bitop3_b32 v22, v38, v39, s3 bitop3:0x36
	v_and_or_b32 v22, v22, 7, v41
	v_lshlrev_b32_e32 v22, 4, v22
	s_cmp_lg_u32 s14, 16
	v_lshl_add_u64 v[50:51], s[4:5], 0, v[22:23]
	v_or_b32_e32 v22, s15, v38
	s_cselect_b64 vcc, -1, 0
	v_cndmask_b32_e32 v100, 64, v22, vcc
	v_bitop3_b32 v22, v38, v39, s15 bitop3:0x36
	v_and_or_b32 v22, v22, 7, v41
	v_lshlrev_b32_e32 v22, 4, v22
	s_cmp_lg_u32 s16, 16
	v_lshl_add_u64 v[52:53], s[4:5], 0, v[22:23]
	v_or_b32_e32 v22, s17, v38
	s_cselect_b64 vcc, -1, 0
	v_cndmask_b32_e32 v101, 64, v22, vcc
	v_bitop3_b32 v22, v38, v39, s17 bitop3:0x36
	v_and_or_b32 v22, v22, 7, v41
	v_lshlrev_b32_e32 v22, 4, v22
	v_lshl_add_u64 v[54:55], s[4:5], 0, v[22:23]
	v_xor_b32_e32 v22, v38, v20
	s_movk_i32 s10, 0x3700
	v_or_b32_e32 v22, v22, v41
	v_lshlrev_b32_e32 v41, 5, v9
	v_lshrrev_b32_e32 v45, 7, v42
	v_cmp_gt_u32_e64 s[0:1], 16, v40
	v_or_b32_e32 v103, v27, v41
	v_lshl_add_u32 v104, v40, 2, s71
	v_add_u32_e32 v40, s71, v41
	v_lshrrev_b32_e32 v41, 2, v9
	v_mul_lo_u32 v45, v45, s10
	v_or_b32_e32 v41, v90, v41
	v_add_u32_e32 v67, 0, v45
	v_bfe_u32 v45, v42, 3, 4
	v_mul_u32_u24_e32 v41, 0x48, v41
	v_and_b32_e32 v21, 12, v21
	v_mul_u32_u24_e32 v45, 0x48, v45
	v_or_b32_e32 v24, s11, v90
	v_add_lshl_u32 v105, v21, v41, 1
	v_lshl_or_b32 v21, v89, 6, v8
	v_add_lshl_u32 v8, v45, v8, 1
	v_mov_b32_e32 v45, v10
	v_and_b32_e32 v26, 7, v25
	v_lshl_add_u64 v[60:61], s[6:7], 0, v[44:45]
	v_cmp_eq_u32_e64 s[6:7], 0, v42
	v_lshrrev_b32_e32 v42, 3, v24
	v_and_b32_e32 v62, 8, v42
	v_bitop3_b32 v63, v42, v26, 5 bitop3:0x6c
	v_or_b32_e32 v63, v63, v62
	v_lshlrev_b32_e32 v68, 4, v63
	v_add_u32_e32 v63, 64, v24
	v_bitop3_b32 v45, v42, v25, 7 bitop3:0x78
	v_lshrrev_b32_e32 v64, 3, v63
	v_xor_b32_e32 v69, v42, v20
	v_bitop3_b32 v42, v42, v20, 5 bitop3:0x6c
	v_and_b32_e32 v65, 8, v64
	v_or_b32_e32 v42, v42, v62
	v_bitop3_b32 v62, v64, v20, 5 bitop3:0x6c
	v_or_b32_e32 v62, v62, v65
	v_lshlrev_b32_e32 v108, 4, v69
	v_lshlrev_b32_e32 v69, 4, v62
	v_or_b32_e32 v62, 16, v24
	v_lshlrev_b32_e32 v22, 4, v22
	v_lshlrev_b32_e32 v71, 1, v63
	v_lshrrev_b32_e32 v63, 3, v62
	v_lshl_add_u64 v[56:57], s[4:5], 0, v[22:23]
	v_xor_b32_e32 v22, v88, v20
	v_bitop3_b32 v26, v64, v26, 5 bitop3:0x6c
	v_bitop3_b32 v64, v63, v25, 7 bitop3:0x78
	v_lshlrev_b32_e32 v22, 4, v22
	v_or_b32_e32 v26, v26, v65
	v_lshlrev_b32_e32 v111, 4, v64
	v_and_b32_e32 v64, 8, v63
	v_bitop3_b32 v65, v63, v25, 7 bitop3:0x28
	s_movk_i32 s18, 0x48
	v_lshl_add_u64 v[58:59], s[8:9], 0, v[22:23]
	v_or_b32_e32 v23, s11, v9
	v_or_b32_e32 v65, v65, v64
	v_mul_u32_u24_e32 v30, 0x48, v11
	v_mul_u32_u24_e32 v31, 0x48, v9
	v_lshlrev_b32_e32 v97, 2, v11
	v_or_b32_e32 v22, 16, v90
	v_lshlrev_b32_e32 v72, 4, v65
	v_add_u32_e32 v65, 0x50, v24
	v_mul_lo_u32 v23, v23, s18
	v_mad_u32_u24 v11, v11, s18, 32
	v_lshlrev_b32_e32 v70, 1, v24
	v_add_lshl_u32 v109, v24, v30, 1
	v_add_lshl_u32 v110, v24, v31, 1
	v_lshrrev_b32_e32 v73, 3, v65
	v_xor_b32_e32 v75, v63, v20
	v_bitop3_b32 v63, v63, v20, 7 bitop3:0x6c
	v_add_lshl_u32 v113, v62, v30, 1
	v_add_lshl_u32 v115, v30, v90, 1
	v_add_lshl_u32 v116, v22, v30, 1
	v_add_u32_e32 v30, 0x480, v23
	v_add_lshl_u32 v119, v11, v90, 1
	v_add_lshl_u32 v120, v11, v22, 1
	v_or_b32_e32 v11, 32, v90
	v_lshlrev_b32_e32 v123, 2, v24
	v_or_b32_e32 v24, 1, v90
	v_cmp_eq_u32_e32 vcc, v90, v9
	v_lshlrev_b32_e32 v106, 5, v20
	v_and_b32_e32 v74, 8, v73
	v_bitop3_b32 v25, v73, v25, 7 bitop3:0x28
	v_or_b32_e32 v63, v63, v64
	v_bitop3_b32 v20, v73, v20, 7 bitop3:0x6c
	v_lshlrev_b32_e32 v73, 1, v62
	v_add_lshl_u32 v114, v62, v31, 1
	v_add_lshl_u32 v118, v30, v90, 1
	v_add_lshl_u32 v122, v11, v30, 1
	v_lshlrev_b32_e32 v124, 2, v62
	v_or_b32_e32 v30, 2, v90
	v_cndmask_b32_e64 v62, 0, 1.0, vcc
	v_cmp_eq_u32_e32 vcc, v24, v9
	v_lshlrev_b32_e32 v112, 4, v75
	v_lshlrev_b32_e32 v75, 4, v63
	v_add_lshl_u32 v117, v90, v23, 1
	v_add_lshl_u32 v121, v11, v23, 1
	v_add_lshl_u32 v125, v90, v31, 1
	v_add_lshl_u32 v23, v11, v31, 1
	v_or_b32_e32 v31, 3, v90
	v_cndmask_b32_e64 v63, 0, 1.0, vcc
	v_cmp_eq_u32_e32 vcc, v30, v9
	v_cmp_eq_u32_e64 s[4:5], 0, v9
	v_mad_u32_u24 v37, v9, s18, 16
	v_cmp_lt_u32_e64 s[8:9], v90, v9
	v_cmp_gt_u32_e64 s[10:11], v90, v9
	v_cmp_lt_u32_e64 s[12:13], v24, v9
	v_cmp_lt_u32_e64 s[14:15], v30, v9
	v_cmp_gt_u32_e64 s[16:17], v30, v9
	v_cmp_lt_u32_e64 s[18:19], v31, v9
	v_cmp_gt_u32_e64 s[20:21], v31, v9
	v_cndmask_b32_e64 v64, 0, 1.0, vcc
	v_cmp_eq_u32_e32 vcc, v31, v9
	v_lshlrev_b32_e32 v9, 2, v9
	v_lshl_add_u32 v24, v38, 10, s97
	s_mov_b32 s3, 0xdc00
	v_add3_u32 v126, v24, v9, s3
	v_and_b32_e32 v9, 3, v39
	s_movk_i32 s25, 0x2400
	v_lshlrev_b32_e32 v43, 2, v21
	v_lshlrev_b32_e32 v21, 1, v21
	v_lshl_or_b32 v9, v9, 3, s29
	v_lshlrev_b32_e32 v24, 1, v41
	s_waitcnt lgkmcnt(0)
	s_barrier
	v_lshlrev_b32_e32 v66, 2, v89
	v_or_b32_e32 v25, v25, v74
	v_or_b32_e32 v20, v20, v74
	v_add3_u32 v128, v9, v24, s25
	v_mov_b32_e32 v9, 0x3540
	v_add_u32_e32 v151, v67, v8
	v_add_u32_e32 v8, 0, v21
	s_mov_b32 s39, 0
	v_and_b32_e32 v102, 48, v39
	v_lshlrev_b32_e32 v26, 4, v26
	v_lshlrev_b32_e32 v42, 4, v42
	v_lshlrev_b32_e32 v25, 4, v25
	v_lshlrev_b32_e32 v20, 4, v20
	v_lshlrev_b32_e32 v74, 1, v65
	v_add_lshl_u32 v22, v37, v90, 1
	v_add_lshl_u32 v11, v11, v37, 1
	v_writelane_b32 v255, s97, 32
	v_lshl_or_b32 v129, v38, 4, v9
	s_add_i32 s3, 0, 0x15c00
	s_add_i32 s88, s22, 0
	s_add_i32 s89, s23, 0
	s_add_i32 s90, s24, 0
	v_add_u32_e32 v9, 0, v66
	v_add_u32_e32 v152, 0x12800, v8
	v_mbcnt_lo_u32_b32 v8, -1, 0
	s_mov_b64 s[52:53], s[38:39]
	v_add_u32_e32 v107, s70, v89
	v_lshlrev_b32_e32 v45, 4, v45
	v_cndmask_b32_e64 v65, 0, 1.0, vcc
	v_add_u32_e32 v127, 0x2d00, v103
	v_writelane_b32 v255, s29, 44
	v_or_b32_e32 v130, 0x3500, v102
	v_add_u32_e32 v131, v28, v68
	v_add_u32_e32 v132, v28, v26
	v_add_u32_e32 v133, v29, v42
	v_add_u32_e32 v134, v29, v69
	v_add_u32_e32 v135, s3, v70
	v_add_u32_e32 v136, s3, v71
	s_mov_b32 s86, 0x4038aa3b
	s_add_i32 s67, 0, 0x10000
	v_add_u32_e32 v137, v28, v72
	v_add_u32_e32 v138, v28, v25
	v_add_u32_e32 v139, v29, v75
	v_add_u32_e32 v140, v29, v20
	v_add_u32_e32 v141, s3, v73
	v_add_u32_e32 v142, s3, v74
	v_add_u32_e32 v143, v32, v33
	v_add_u32_e32 v145, v34, v35
	s_mov_b32 s87, 0xbfb8aa3b
	v_add_u32_e32 v146, v36, v44
	s_add_i32 s88, s88, 0x23900
	s_add_i32 s89, s89, 0x23900
	s_add_i32 s90, s90, 0x23900
	s_add_i32 s91, 0, 0x27900
	s_add_i32 s92, s81, 0x400
	s_add_i32 s93, s81, 0x800
	s_add_i32 s94, s81, 0xc00
	s_add_i32 s95, s81, 0x1400
	s_add_i32 s96, s81, 0x1800
	s_add_i32 s97, s81, 0x1c00
	s_add_i32 s3, 0, 0x16100
	s_add_i32 s69, 0, 0x18500
	v_mov_b32_e32 v147, 0xbf92477c
	v_add_u32_e32 v148, v40, v27
	s_xor_b64 s[54:55], s[26:27], -1
	v_add_u32_e32 v149, 0, v43
	v_add_u32_e32 v150, 0x12400, v9
	s_and_b64 vcc, exec, s[36:37]
	s_cbranch_vccnz .Lds_noswap
	s_and_b64 vcc, exec, s[54:55]
	s_cbranch_vccnz .Lds_swap_hi
	v_add_u32_e32 v149, 0x2000, v149
	v_add_u32_e32 v150, 0x80, v150
	v_add_u32_e32 v151, 0x6e00, v151
	v_add_u32_e32 v152, 0x1000, v152
	v_add_u32_e32 v107, 32, v107
	s_branch .Lds_noswap
.Lds_swap_hi:
	v_add_u32_e32 v149, 0xffffe000, v149
	v_add_u32_e32 v150, 0xffffff80, v150
	v_add_u32_e32 v151, 0xffff9200, v151
	v_add_u32_e32 v152, 0xfffff000, v152
	v_add_u32_e32 v107, 0xffffffe0, v107
.Lds_noswap:
	v_mov_b32_e32 v153, 0x3a27c5ac
	v_mbcnt_hi_u32_b32 v144, -1, v8
	v_add_u32_e32 v154, s71, v22
	v_add_u32_e32 v155, s71, v23
	v_add_u32_e32 v156, s71, v11
	s_mov_b32 s33, s28
	s_mov_b32 s29, 0
	v_add_u32_e32 v211, v93, v45
	v_add_u32_e32 v233, s67, v119
	v_add_u32_e32 v210, v96, v108
	v_add_u32_e32 v224, s71, v114
	v_add_u32_e32 v228, s67, v116
	v_add_u32_e32 v232, s69, v118
	v_add_u32_e32 v214, s71, v110
	v_add_u32_e32 v223, s67, v113
	v_add_u32_e32 v212, v91, v45
	v_add_u32_e32 v213, s67, v109
	v_add_u32_e32 v239, 0x12600, v97
	v_add_u32_e32 v235, s3, v121
	v_add_u32_e32 v219, v93, v111
	v_add_u32_e32 v208, v94, v108
	v_add_u32_e32 v220, v91, v111
	v_xor_b32_e32 v243, 32, v144
	v_and_b32_e32 v241, 64, v144
	v_add_u32_e32 v21, 64, v241
	v_cmp_lt_i32_e32 vcc, v243, v21
	s_nop 1
	v_cndmask_b32_e32 v20, v144, v243, vcc
	v_lshlrev_b32_e32 v222, 2, v20
	v_xor_b32_e32 v242, 16, v144
	v_cmp_lt_i32_e32 vcc, v242, v21
	s_nop 1
	v_cndmask_b32_e32 v22, v144, v242, vcc
	v_lshlrev_b32_e32 v221, 2, v22
	v_add_u32_e32 v237, s3, v122
	v_add_u32_e32 v231, s3, v118
	v_add_u32_e32 v207, v92, v45
	v_or_b32_e32 v240, v102, v241
	v_add_u32_e32 v217, v95, v112
	v_add_u32_e32 v215, v92, v111
	v_add_u32_e32 v227, s67, v115
	v_add_u32_e32 v236, s69, v121
	v_add_u32_e32 v225, 0x15d80, v44
	v_add_u32_e32 v209, v95, v108
	v_add_u32_e32 v230, s69, v117
	v_add_u32_e32 v218, v96, v112
	v_add_u32_e32 v226, s83, v102
	v_add_u32_e32 v229, s3, v117
	v_add_u32_e32 v216, v94, v112
	v_add_u32_e32 v238, s69, v122
	v_add_u32_e32 v234, s67, v120
	v_mov_b32_e32 v252, 0
	s_waitcnt vmcnt(0)

.LBB0_578:
	s_cmp_eq_u32 s28, s29
	s_waitcnt lgkmcnt(0)
	s_barrier
	s_cselect_b64 s[24:25], -1, 0
	s_or_b64 s[24:25], s[54:55], s[24:25]
	s_and_b64 vcc, exec, s[24:25]
	s_cbranch_vccnz .Lds_early
	s_min_u32 s24, s33, 64
	s_lshr_b32 s24, s24, 4
	s_max_u32 s24, s24, 1
	v_mov_b32_e32 v42, v125
	v_mov_b32_e32 v43, v130
	v_mov_b32_e32 v82, v129
	v_mov_b32_e32 v83, v128
	v_mov_b32_e32 v84, v105
	v_mov_b32_e32 v85, v127
	v_mov_b32_e32 v86, v126
	s_waitcnt lgkmcnt(0)
	s_setprio 2
.LBB0_580:
	ds_read_b128 v[202:205], v82 offset:128
	ds_read_b128 v[186:189], v82 offset:64
	ds_read_b128 v[182:185], v82
	ds_read_b64_tr_b16 v[170:171], v84 offset:7008
	ds_read_b64_tr_b16 v[30:31], v83
	v_add_u32_e32 v83, 0x3700, v83
	ds_read2st64_b64 v[194:197], v85 offset1:1
	ds_read_b128 v[198:201], v43
	ds_read2_b64 v[190:193], v42 offset0:8 offset1:12
	ds_read_b64_tr_b16 v[162:163], v84 offset:6944
	ds_read2_b64 v[178:181], v42 offset1:4
	ds_read_b64_tr_b16 v[166:167], v84 offset:6976
	ds_read_b64_tr_b16 v[158:159], v84 offset:6912
	ds_read_b64_tr_b16 v[38:39], v84 offset:4608
	s_waitcnt lgkmcnt(12)
	v_pk_mul_f32 v[16:17], v[16:17], v[202:203]
	v_add_u32_e32 v202, 0x800, v42
	v_add_u32_e32 v42, 0x3700, v42
	v_pk_mul_f32 v[18:19], v[18:19], v[204:205]
	s_waitcnt lgkmcnt(11)
	v_pk_mul_f32 v[14:15], v[14:15], v[188:189]
	v_cvt_pk_f16_f32 v189, v18, v19
	v_cvt_pk_f16_f32 v188, v16, v17
	s_waitcnt lgkmcnt(10)
	v_pk_mul_f32 v[6:7], v[6:7], v[184:185]
	v_pk_mul_f32 v[4:5], v[4:5], v[182:183]
	ds_read2st64_b64 v[182:185], v85 offset0:2 offset1:3
	v_add_u32_e32 v85, 0x3700, v85
	s_waitcnt lgkmcnt(9)
	v_mfma_f32_16x16x16_f16 v[170:173], v[170:171], v[30:31], v[16:19]
	v_pk_mul_f32 v[12:13], v[12:13], v[186:187]
	s_waitcnt lgkmcnt(8)
	v_mfma_f32_16x16x16_f16 v[16:19], v[194:195], v[30:31], 0
	s_waitcnt lgkmcnt(7)
	v_mul_f32_e64 v2, v2, v200
	v_mul_f32_e64 v3, v3, v201
	v_pk_mul_f32 v[0:1], v[0:1], v[198:199]
	v_cvt_pk_f16_f32 v187, v14, v15
	v_cvt_pk_f16_f32 v186, v12, v13
	v_cvt_pk_f16_f32 v201, v6, v7
	v_cvt_pk_f16_f32 v199, v2, v3
	v_cvt_pk_f16_f32 v200, v4, v5
	v_cvt_pk_f16_f32 v198, v0, v1
	s_waitcnt lgkmcnt(6)
	v_mfma_f32_16x16x32_f16 v[190:193], v[190:193], v[186:189], 0
	s_waitcnt lgkmcnt(5)
	v_mfma_f32_16x16x16_f16 v[162:165], v[162:163], v[30:31], v[4:7]
	s_waitcnt lgkmcnt(4)
	v_mfma_f32_16x16x32_f16 v[4:7], v[178:181], v[198:201], v[16:19]
	s_waitcnt lgkmcnt(3)
	v_mfma_f32_16x16x16_f16 v[12:15], v[166:167], v[30:31], v[12:15]
	ds_read_b64_tr_b16 v[174:175], v84 offset:4640
	ds_read2_b64 v[166:169], v202 offset0:40 offset1:44
	ds_read_b64_tr_b16 v[22:23], v84 offset:4672
	s_nop 3
	v_pk_add_f32 v[6:7], v[6:7], v[192:193]
	v_pk_add_f32 v[4:5], v[4:5], v[190:191]
	v_cvt_pk_f16_f32 v35, v6, v7
	v_cvt_pk_f16_f32 v34, v4, v5
	s_waitcnt lgkmcnt(3)
	s_nop 0
	v_mfma_f32_16x16x16_f16 v[4:7], v[184:185], v[34:35], 0
	v_mfma_f32_16x16x16_f16 v[158:161], v[158:159], v[30:31], v[0:3]
	s_nop 6
	s_waitcnt lgkmcnt(1)
	v_mfma_f32_16x16x32_f16 v[0:3], v[166:169], v[186:189], 0
	v_cvt_pk_f16_f32 v19, -v6, -v7
	v_cvt_pk_f16_f32 v18, -v4, -v5
	v_mfma_f32_16x16x16_f16 v[6:9], v[196:197], v[30:31], 0
	s_add_i32 s24, s24, -1
	v_mfma_f32_16x16x16_f16 v[30:33], v[38:39], v[18:19], v[158:161]
	ds_read_b64_tr_b16 v[26:27], v84 offset:4704
	v_add_u32_e32 v84, 0x3700, v84
	ds_read_b128 v[38:41], v43 offset:256
	v_add_u32_e32 v43, 0x3700, v43
	s_nop 0
	ds_read_b128 v[158:161], v82 offset:256
	v_mfma_f32_16x16x16_f16 v[34:37], v[174:175], v[18:19], v[162:165]
	s_waitcnt lgkmcnt(3)
	v_mfma_f32_16x16x16_f16 v[12:15], v[22:23], v[18:19], v[12:15]
	ds_read_b128 v[22:25], v82 offset:320
	ds_read_b128 v[162:165], v82 offset:384
	v_add_u32_e32 v82, 0x3700, v82
	v_mfma_f32_16x16x16_f16 v[166:169], v[182:183], v[18:19], v[0:3]
	s_waitcnt lgkmcnt(2)
	v_pk_mul_f32 v[4:5], v[158:159], v[34:35]
	ds_read2_b64 v[0:3], v202 offset0:32 offset1:36
	v_mfma_f32_16x16x16_f16 v[26:29], v[26:27], v[18:19], v[170:173]
	s_waitcnt lgkmcnt(2)
	v_pk_mul_f32 v[14:15], v[24:25], v[14:15]
	v_pk_mul_f32 v[12:13], v[22:23], v[12:13]
	s_waitcnt lgkmcnt(0)
	v_mfma_f32_16x16x32_f16 v[170:173], v[0:3], v[198:201], v[6:9]
	v_mul_f32_e64 v2, v40, v32
	v_mul_f32_e64 v3, v41, v33
	v_pk_mul_f32 v[0:1], v[38:39], v[30:31]
	v_pk_mul_f32 v[6:7], v[160:161], v[36:37]
	v_pk_mul_f32 v[18:19], v[164:165], v[28:29]
	v_pk_mul_f32 v[16:17], v[162:163], v[26:27]
	s_nop 1
	v_pk_add_f32 v[20:21], v[170:171], v[166:167]
	v_pk_add_f32 v[8:9], v[172:173], v[168:169]
	ds_write2st64_b32 v86, v20, v21 offset1:1
	ds_write2st64_b32 v86, v8, v9 offset0:2 offset1:3
	v_add_u32_e32 v86, 0x1000, v86
	s_cmp_lg_u32 s24, 2
	s_cbranch_scc1 .Lds_nomid
	s_waitcnt lgkmcnt(0)
	s_barrier
.Lds_nomid:
	s_cmp_lg_u32 s24, 0
	s_cbranch_scc1 .LBB0_580
	s_setprio 0

.Lds_after:
	s_and_b32 s22, s29, 0xc0
	s_cmpk_lg_i32 s22, 0xc0
	s_cselect_b64 s[22:23], -1, 0
	s_or_b64 s[24:25], s[36:37], s[22:23]
	s_mov_b64 s[22:23], -1
	s_and_b64 vcc, exec, s[24:25]
	s_cbranch_vccnz .LBB0_589
	s_lshr_b32 s29, s29, 2
	s_and_b32 s29, s29, 0x1fffffc0
	s_add_i32 s29, s29, s85
	s_lshl_b32 s29, s29, 2
	v_readlane_b32 s24, v255, 34
	v_readlane_b32 s25, v255, 35
	v_mov_b32_e32 v250, s29
	v_mov_b32_e32 v251, 0
	s_nop 1
	v_lshl_add_u64 v[250:251], s[24:25], 0, v[250:251]
	s_and_saveexec_b64 s[22:23], s[6:7]
	v_mov_b32_e32 v252, 1
	s_mov_b64 exec, s[22:23]
	s_branch .LBB0_590

.Lds_early:
	s_and_b64 vcc, exec, s[36:37]
	s_cbranch_vccnz .LBB0_581
	s_barrier
	s_and_saveexec_b64 s[24:25], s[22:23]
	s_cbranch_execz .Lds_e583
	ds_read_b128 v[20:23], v149 offset:56320
	s_waitcnt lgkmcnt(0)
	ds_read2st64_b32 v[8:9], v150 offset1:1
	ds_read_b128 v[24:27], v149 offset:56336
	s_add_i32 s22, 0, 0x14800
	ds_read_b128 v[28:31], v151 offset:9216
	ds_read_b128 v[32:35], v152
	v_add_f32_e32 v11, 0, v20
	s_waitcnt lgkmcnt(0)
	v_add_f32_e32 v8, v8, v9
	v_add_f32_e32 v9, v21, v11
	v_add_f32_e32 v9, v22, v9
	v_add_f32_e32 v9, v23, v9
	v_add_f32_e32 v9, v24, v9
	v_add_f32_e32 v9, v25, v9
	v_add_f32_e32 v9, v26, v9
	v_add_f32_e32 v9, v27, v9
	v_cvt_f32_f16_e32 v164, v28
	v_cvt_f32_f16_sdwa v165, v28 dst_sel:DWORD dst_unused:UNUSED_PAD src0_sel:WORD_1
	v_add_f32_dpp v9, v9, v9 quad_perm:[1,0,3,2] row_mask:0xf bank_mask:0xf bound_ctrl:1
	v_cvt_f32_f16_e32 v28, v29
	v_cvt_f32_f16_sdwa v29, v29 dst_sel:DWORD dst_unused:UNUSED_PAD src0_sel:WORD_1
	v_add_f32_dpp v9, v9, v9 quad_perm:[2,3,0,1] row_mask:0xf bank_mask:0xf bound_ctrl:1
	v_cvt_f32_f16_e32 v166, v32
	v_cvt_f32_f16_sdwa v167, v32 dst_sel:DWORD dst_unused:UNUSED_PAD src0_sel:WORD_1
	v_add_f32_dpp v9, v9, v9 row_half_mirror row_mask:0xf bank_mask:0xf bound_ctrl:1
	v_mul_f32_e32 v86, 0x3c800000, v9
	v_pk_add_f32 v[20:21], v[20:21], v[86:87] op_sel_hi:[1,0] neg_lo:[0,1] neg_hi:[0,1]
	v_add_u32_e32 v9, s22, v106
	v_pk_mul_f32 v[162:163], v[20:21], v[20:21]
	v_pk_add_f32 v[22:23], v[22:23], v[86:87] op_sel_hi:[1,0] neg_lo:[0,1] neg_hi:[0,1]
	ds_read_b128 v[36:39], v9 offset:2304
	ds_read_b128 v[40:43], v9 offset:2320
	ds_read_b128 v[82:85], v9 offset:2560
	ds_read_b128 v[158:161], v9 offset:2576
	v_pk_mul_f32 v[168:169], v[22:23], v[22:23]
	v_add_f32_e32 v9, v162, v163
	v_pk_add_f32 v[24:25], v[24:25], v[86:87] op_sel_hi:[1,0] neg_lo:[0,1] neg_hi:[0,1]
	v_add_f32_e32 v9, v168, v9
	v_pk_mul_f32 v[170:171], v[24:25], v[24:25]
	v_add_f32_e32 v9, v169, v9
	v_pk_add_f32 v[26:27], v[26:27], v[86:87] op_sel_hi:[1,0] neg_lo:[0,1] neg_hi:[0,1]
	v_add_f32_e32 v9, v170, v9
	v_pk_mul_f32 v[86:87], v[26:27], v[26:27]
	v_add_f32_e32 v9, v171, v9
	v_add_f32_e32 v9, v86, v9
	v_add_f32_e32 v9, v87, v9
	v_cvt_f32_f16_e32 v32, v33
	v_cvt_f32_f16_sdwa v33, v33 dst_sel:DWORD dst_unused:UNUSED_PAD src0_sel:WORD_1
	v_add_f32_dpp v9, v9, v9 quad_perm:[1,0,3,2] row_mask:0xf bank_mask:0xf bound_ctrl:1
	v_cvt_f32_f16_e32 v172, v30
	v_cvt_f32_f16_sdwa v173, v30 dst_sel:DWORD dst_unused:UNUSED_PAD src0_sel:WORD_1
	v_add_f32_dpp v9, v9, v9 quad_perm:[2,3,0,1] row_mask:0xf bank_mask:0xf bound_ctrl:1
	v_cvt_f32_f16_e32 v162, v34
	v_cvt_f32_f16_sdwa v163, v34 dst_sel:DWORD dst_unused:UNUSED_PAD src0_sel:WORD_1
	v_add_f32_dpp v9, v9, v9 row_half_mirror row_mask:0xf bank_mask:0xf bound_ctrl:1
	v_fmamk_f32 v9, v9, 0x3c800000, v153
	v_rsq_f32_e32 v86, v9
	s_nop 0
	v_pk_mul_f32 v[20:21], v[20:21], v[86:87] op_sel_hi:[1,0]
	v_pk_mul_f32 v[22:23], v[22:23], v[86:87] op_sel_hi:[1,0]
	s_waitcnt lgkmcnt(0)
	v_pk_fma_f32 v[20:21], v[36:37], v[20:21], v[82:83]
	v_pk_fma_f32 v[22:23], v[38:39], v[22:23], v[84:85]
	v_pk_fma_f32 v[20:21], v[8:9], v[164:165], v[20:21] op_sel_hi:[0,1,1]
	v_pk_fma_f32 v[22:23], v[8:9], v[28:29], v[22:23] op_sel_hi:[0,1,1]
	v_pk_mul_f32 v[20:21], v[20:21], v[166:167]
	v_pk_mul_f32 v[22:23], v[22:23], v[32:33]
	v_cvt_pk_f16_f32 v20, v20, v21
	v_cvt_pk_f16_f32 v21, v22, v23
	v_pk_mul_f32 v[22:23], v[24:25], v[86:87] op_sel_hi:[1,0]
	v_cvt_f32_f16_e32 v24, v31
	v_cvt_f32_f16_sdwa v25, v31 dst_sel:DWORD dst_unused:UNUSED_PAD src0_sel:WORD_1
	v_cvt_f32_f16_e32 v28, v35
	v_cvt_f32_f16_sdwa v29, v35 dst_sel:DWORD dst_unused:UNUSED_PAD src0_sel:WORD_1
	v_pk_mul_f32 v[26:27], v[26:27], v[86:87] op_sel_hi:[1,0]
	v_pk_fma_f32 v[22:23], v[40:41], v[22:23], v[158:159]
	v_pk_fma_f32 v[26:27], v[42:43], v[26:27], v[160:161]
	v_pk_fma_f32 v[22:23], v[8:9], v[172:173], v[22:23] op_sel_hi:[0,1,1]
	v_pk_fma_f32 v[8:9], v[8:9], v[24:25], v[26:27] op_sel_hi:[0,1,1]
	v_pk_mul_f32 v[22:23], v[22:23], v[162:163]
	v_pk_mul_f32 v[8:9], v[8:9], v[28:29]
	v_cvt_pk_f16_f32 v22, v22, v23
	v_cvt_pk_f16_f32 v23, v8, v9
	v_add_u32_e32 v8, s29, v107
	v_ashrrev_i32_e32 v9, 31, v8
	v_lshlrev_b64 v[8:9], 11, v[8:9]
	v_lshl_add_u64 v[8:9], v[60:61], 0, v[8:9]
	global_store_dwordx4 v[8:9], v[20:23], off sc1
	s_nop 1
.Lds_e583:
	s_or_b64 exec, exec, s[24:25]
	s_waitcnt vmcnt(1)
	s_waitcnt lgkmcnt(0)
	s_barrier
	s_branch .Lds_after
